# v42 + panel hand-off waits (P4/P5/P6 starts): panel counter requested before the own signal's store drain; >= 3 means the three partners are done, poll round trip skipped (acquire kept)
# baseline (speedup 1.0000x reference)
.LBB0_583:
	s_mov_b64 s[100:101], exec
	v_readlane_b32 s98, v251, 41
	v_readlane_b32 s99, v251, 42
	s_and_b64 s[98:99], s[100:101], s[98:99]
	s_mov_b64 exec, s[98:99]
	s_cbranch_execz .Lmy_pm3_skip
	v_readlane_b32 s98, v251, 62
	v_readlane_b32 s99, v251, 61
	s_lshl_b32 s98, s98, 3
	s_and_b32 s99, s99, 7
	s_or_b32 s98, s98, s99
	s_lshl_b32 s98, s98, 8
	v_mov_b32_e32 v252, s98
	v_readlane_b32 s98, v251, 20
	v_readlane_b32 s99, v251, 21
	s_add_u32 s98, s98, 0x18000
	s_addc_u32 s99, s99, 0
	global_load_dword v254, v252, s[98:99] sc1
.Lmy_pm3_skip:
	s_mov_b64 exec, s[100:101]
	s_waitcnt vmcnt(0)
	s_waitcnt lgkmcnt(0)
	s_barrier
	s_mov_b64 s[2:3], exec
	v_readlane_b32 s4, v251, 41
	v_readlane_b32 s5, v251, 42
	s_and_b64 s[4:5], s[2:3], s[4:5]
	s_mov_b64 exec, s[4:5]
	s_cbranch_execz .LBB0_586
	s_mov_b64 s[4:5], exec
	v_mbcnt_lo_u32_b32 v2, s4, 0
	v_mbcnt_hi_u32_b32 v2, s5, v2
	v_cmp_eq_u32_e32 vcc, 0, v2
	s_and_b64 s[18:19], exec, vcc
	s_mov_b64 exec, s[18:19]
	s_cbranch_execz .LBB0_586
	s_bcnt1_i32_b64 s1, s[4:5]
	v_mov_b32_e32 v2, 0
	v_mov_b32_e32 v3, s1
	global_atomic_add v2, v3, s[6:7]

.LBB0_594:
	v_readlane_b32 s36, v251, 6
	v_readlane_b32 s48, v251, 18
	v_readlane_b32 s49, v251, 19
	s_add_u32 s28, s6, 0x4000
	v_readlane_b32 s50, v251, 20
	v_readlane_b32 s51, v251, 21
	s_mov_b64 s[20:21], s[48:49]
	s_addc_u32 s29, s7, 0
	s_mov_b64 s[22:23], s[50:51]
	s_add_u32 s20, s22, 0x28100
	s_addc_u32 s21, s23, 0
	s_add_u32 s22, s22, 0x13800000
	s_addc_u32 s23, s23, 0
	s_cmp_lt_i32 s72, 5
	s_cselect_b64 s[2:3], -1, 0
	s_cmp_gt_i32 s73, 4
	s_cselect_b64 s[4:5], -1, 0
	s_and_b64 s[2:3], s[2:3], s[4:5]
	s_andn2_b64 vcc, exec, s[2:3]
	v_cmp_gt_u32_e64 s[2:3], 64, v0
	v_readlane_b32 s75, v251, 62
	v_readlane_b32 s37, v251, 7
	v_readlane_b32 s38, v251, 8
	v_readlane_b32 s39, v251, 9
	v_readlane_b32 s40, v251, 10
	v_readlane_b32 s41, v251, 11
	v_readlane_b32 s42, v251, 12
	v_readlane_b32 s43, v251, 13
	v_readlane_b32 s44, v251, 14
	v_readlane_b32 s45, v251, 15
	v_readlane_b32 s46, v251, 16
	v_readlane_b32 s47, v251, 17
	s_cbranch_vccnz .LBB0_653
	s_and_saveexec_b64 s[4:5], s[2:3]
	s_cbranch_execz .LBB0_607
	v_readfirstlane_b32 s98, v254
	s_cmpk_gt_u32 s98, 2
	s_cbranch_scc1 .LBB0_606
	s_memrealtime s[18:19]
	v_mov_b32_e32 v4, 0
	v_mov_b64_e32 v[2:3], 0x1e8481
	s_branch .LBB0_599

.LBB0_633:
	s_mov_b64 s[100:101], exec
	v_readlane_b32 s98, v251, 41
	v_readlane_b32 s99, v251, 42
	s_and_b64 s[98:99], s[100:101], s[98:99]
	s_mov_b64 exec, s[98:99]
	s_cbranch_execz .Lmy_pm4_skip
	v_readlane_b32 s98, v251, 62
	v_readlane_b32 s99, v251, 61
	s_lshl_b32 s98, s98, 3
	s_and_b32 s99, s99, 7
	s_or_b32 s98, s98, s99
	s_lshl_b32 s98, s98, 8
	v_mov_b32_e32 v252, s98
	v_readlane_b32 s98, v251, 20
	v_readlane_b32 s99, v251, 21
	s_add_u32 s98, s98, 0x1c000
	s_addc_u32 s99, s99, 0
	global_load_dword v254, v252, s[98:99] sc1
.Lmy_pm4_skip:
	s_mov_b64 exec, s[100:101]
	s_mov_b64 s[100:101], exec
	v_readlane_b32 s98, v251, 41
	v_readlane_b32 s99, v251, 42
	s_and_b64 s[98:99], s[100:101], s[98:99]
	s_mov_b64 exec, s[98:99]
	s_cbranch_execz .Lmy_pf4_skip
	v_readlane_b32 s98, v251, 20
	v_readlane_b32 s99, v251, 21
	s_add_u32 s98, s98, 0x28000
	s_addc_u32 s99, s99, 0
	v_mov_b32_e32 v252, 0
	global_load_dword v253, v252, s[98:99] sc1

.Lmy_t5b_skip:
	v_cmp_gt_u32_e64 s[2:3], 64, v0
	s_and_saveexec_b64 s[4:5], s[2:3]
	s_cbranch_execz .LBB0_666
	v_readfirstlane_b32 s98, v254
	s_cmpk_gt_u32 s98, 2
	s_cbranch_scc1 .LBB0_665
	s_memrealtime s[6:7]
	v_mov_b32_e32 v4, 0
	v_mov_b64_e32 v[2:3], 0x1e8481
	s_branch .LBB0_658

.LBB0_707:
	s_mov_b64 s[100:101], exec
	v_readlane_b32 s98, v251, 41
	v_readlane_b32 s99, v251, 42
	s_and_b64 s[98:99], s[100:101], s[98:99]
	s_mov_b64 exec, s[98:99]
	s_cbranch_execz .Lmy_pm5_skip
	v_readlane_b32 s98, v251, 62
	v_readlane_b32 s99, v251, 61
	s_lshl_b32 s98, s98, 3
	s_and_b32 s99, s99, 7
	s_or_b32 s98, s98, s99
	s_lshl_b32 s98, s98, 8
	v_mov_b32_e32 v252, s98
	v_readlane_b32 s98, v251, 20
	v_readlane_b32 s99, v251, 21
	s_add_u32 s98, s98, 0x20000
	s_addc_u32 s99, s99, 0
	global_load_dword v254, v252, s[98:99] sc1
.Lmy_pm5_skip:
	s_mov_b64 exec, s[100:101]
	s_mov_b64 s[100:101], exec
	v_readlane_b32 s98, v251, 41
	v_readlane_b32 s99, v251, 42
	s_and_b64 s[98:99], s[100:101], s[98:99]
	s_mov_b64 exec, s[98:99]
	s_cbranch_execz .Lmy_pf5_skip
	v_readlane_b32 s98, v251, 20
	v_readlane_b32 s99, v251, 21
	s_add_u32 s98, s98, 0x28100
	s_addc_u32 s99, s99, 0
	v_mov_b32_e32 v252, 0
	global_load_dword v253, v252, s[98:99] sc1
